# EpiWo: three fully drained row batches; EpiMerge b==3: single drain after all gate loads (no waits behind stores)
# baseline (speedup 1.0000x reference)
.Lem_b3:
	global_load_dwordx4 v[212:215], v145, s[4:5]
	global_load_dwordx4 v[216:219], v145, s[4:5] offset:256
	s_add_u32 s62, s4, 0x20000
	s_addc_u32 s63, s5, 0
	global_load_dwordx4 v[220:223], v145, s[62:63]
	global_load_dwordx4 v[224:227], v145, s[62:63] offset:256
	s_add_u32 s62, s4, 0x40000
	s_addc_u32 s63, s5, 0
	global_load_dwordx4 v[228:231], v145, s[62:63]
	global_load_dwordx4 v[232:235], v145, s[62:63] offset:256
	s_add_u32 s62, s4, 0x60000
	s_addc_u32 s63, s5, 0
	global_load_dwordx4 v[236:239], v145, s[62:63]
	global_load_dwordx4 v[240:243], v145, s[62:63] offset:256
	s_add_u32 s62, s4, 0x100000
	s_addc_u32 s63, s5, 0
	global_load_dwordx4 v[244:247], v145, s[62:63]
	global_load_dwordx4 v[178:181], v145, s[62:63] offset:256
	s_add_u32 s62, s4, 0x120000
	s_addc_u32 s63, s5, 0
	global_load_dwordx4 v[182:185], v145, s[62:63]
	global_load_dwordx4 v[186:189], v145, s[62:63] offset:256
	s_add_u32 s62, s4, 0x140000
	s_addc_u32 s63, s5, 0
	global_load_dwordx4 v[190:193], v145, s[62:63]
	global_load_dwordx4 v[162:165], v145, s[62:63] offset:256
	s_add_u32 s62, s4, 0x160000
	s_addc_u32 s63, s5, 0
	global_load_dwordx4 v[166:169], v145, s[62:63]
	global_load_dwordx4 v[170:173], v145, s[62:63] offset:256
	s_waitcnt vmcnt(0)
	v_lshlrev_b32_e32 v194, 16, v212
	v_lshlrev_b32_e32 v248, 16, v213
	v_and_b32_e32 v195, 0xffff0000, v212
	v_and_b32_e32 v249, 0xffff0000, v213
	v_pk_mul_f32 v[128:129], v[128:129], v[194:195]
	v_pk_mul_f32 v[130:131], v[130:131], v[248:249]
	v_lshlrev_b32_e32 v194, 16, v214
	v_lshlrev_b32_e32 v248, 16, v215
	v_and_b32_e32 v195, 0xffff0000, v214
	v_and_b32_e32 v249, 0xffff0000, v215
	v_pk_mul_f32 v[124:125], v[124:125], v[194:195]
	v_pk_mul_f32 v[126:127], v[126:127], v[248:249]
	v_cvt_pk_bf16_f32 v212, v128, v129
	v_cvt_pk_bf16_f32 v213, v130, v131
	v_cvt_pk_bf16_f32 v214, v124, v125
	v_cvt_pk_bf16_f32 v215, v126, v127
	global_store_dwordx4 v148, v[212:215], s[30:31]
	v_lshlrev_b32_e32 v194, 16, v216
	v_lshlrev_b32_e32 v248, 16, v217
	v_and_b32_e32 v195, 0xffff0000, v216
	v_and_b32_e32 v249, 0xffff0000, v217
	v_pk_mul_f32 v[96:97], v[96:97], v[194:195]
	v_pk_mul_f32 v[98:99], v[98:99], v[248:249]
	v_lshlrev_b32_e32 v194, 16, v218
	v_lshlrev_b32_e32 v248, 16, v219
	v_and_b32_e32 v195, 0xffff0000, v218
	v_and_b32_e32 v249, 0xffff0000, v219
	v_pk_mul_f32 v[92:93], v[92:93], v[194:195]
	v_pk_mul_f32 v[94:95], v[94:95], v[248:249]
	v_cvt_pk_bf16_f32 v216, v96, v97
	v_cvt_pk_bf16_f32 v217, v98, v99
	v_cvt_pk_bf16_f32 v218, v92, v93
	v_cvt_pk_bf16_f32 v219, v94, v95
	global_store_dwordx4 v148, v[216:219], s[30:31] offset:256
	s_add_u32 s62, s30, 0x8000
	s_addc_u32 s63, s31, 0
	v_lshlrev_b32_e32 v194, 16, v220
	v_lshlrev_b32_e32 v248, 16, v221
	v_and_b32_e32 v195, 0xffff0000, v220
	v_and_b32_e32 v249, 0xffff0000, v221
	v_pk_mul_f32 v[120:121], v[120:121], v[194:195]
	v_pk_mul_f32 v[122:123], v[122:123], v[248:249]
	v_lshlrev_b32_e32 v194, 16, v222
	v_lshlrev_b32_e32 v248, 16, v223
	v_and_b32_e32 v195, 0xffff0000, v222
	v_and_b32_e32 v249, 0xffff0000, v223
	v_pk_mul_f32 v[116:117], v[116:117], v[194:195]
	v_pk_mul_f32 v[118:119], v[118:119], v[248:249]
	v_cvt_pk_bf16_f32 v220, v120, v121
	v_cvt_pk_bf16_f32 v221, v122, v123
	v_cvt_pk_bf16_f32 v222, v116, v117
	v_cvt_pk_bf16_f32 v223, v118, v119
	global_store_dwordx4 v148, v[220:223], s[62:63]
	v_lshlrev_b32_e32 v194, 16, v224
	v_lshlrev_b32_e32 v248, 16, v225
	v_and_b32_e32 v195, 0xffff0000, v224
	v_and_b32_e32 v249, 0xffff0000, v225
	v_pk_mul_f32 v[88:89], v[88:89], v[194:195]
	v_pk_mul_f32 v[90:91], v[90:91], v[248:249]
	v_lshlrev_b32_e32 v194, 16, v226
	v_lshlrev_b32_e32 v248, 16, v227
	v_and_b32_e32 v195, 0xffff0000, v226
	v_and_b32_e32 v249, 0xffff0000, v227
	v_pk_mul_f32 v[84:85], v[84:85], v[194:195]
	v_pk_mul_f32 v[86:87], v[86:87], v[248:249]
	v_cvt_pk_bf16_f32 v224, v88, v89
	v_cvt_pk_bf16_f32 v225, v90, v91
	v_cvt_pk_bf16_f32 v226, v84, v85
	v_cvt_pk_bf16_f32 v227, v86, v87
	global_store_dwordx4 v148, v[224:227], s[62:63] offset:256
	s_add_u32 s62, s30, 0x10000
	s_addc_u32 s63, s31, 0
	v_lshlrev_b32_e32 v194, 16, v228
	v_lshlrev_b32_e32 v248, 16, v229
	v_and_b32_e32 v195, 0xffff0000, v228
	v_and_b32_e32 v249, 0xffff0000, v229
	v_pk_mul_f32 v[112:113], v[112:113], v[194:195]
	v_pk_mul_f32 v[114:115], v[114:115], v[248:249]
	v_lshlrev_b32_e32 v194, 16, v230
	v_lshlrev_b32_e32 v248, 16, v231
	v_and_b32_e32 v195, 0xffff0000, v230
	v_and_b32_e32 v249, 0xffff0000, v231
	v_pk_mul_f32 v[108:109], v[108:109], v[194:195]
	v_pk_mul_f32 v[110:111], v[110:111], v[248:249]
	v_cvt_pk_bf16_f32 v228, v112, v113
	v_cvt_pk_bf16_f32 v229, v114, v115
	v_cvt_pk_bf16_f32 v230, v108, v109
	v_cvt_pk_bf16_f32 v231, v110, v111
	global_store_dwordx4 v148, v[228:231], s[62:63]
	v_lshlrev_b32_e32 v194, 16, v232
	v_lshlrev_b32_e32 v248, 16, v233
	v_and_b32_e32 v195, 0xffff0000, v232
	v_and_b32_e32 v249, 0xffff0000, v233
	v_pk_mul_f32 v[80:81], v[80:81], v[194:195]
	v_pk_mul_f32 v[82:83], v[82:83], v[248:249]
	v_lshlrev_b32_e32 v194, 16, v234
	v_lshlrev_b32_e32 v248, 16, v235
	v_and_b32_e32 v195, 0xffff0000, v234
	v_and_b32_e32 v249, 0xffff0000, v235
	v_pk_mul_f32 v[76:77], v[76:77], v[194:195]
	v_pk_mul_f32 v[78:79], v[78:79], v[248:249]
	v_cvt_pk_bf16_f32 v232, v80, v81
	v_cvt_pk_bf16_f32 v233, v82, v83
	v_cvt_pk_bf16_f32 v234, v76, v77
	v_cvt_pk_bf16_f32 v235, v78, v79
	global_store_dwordx4 v148, v[232:235], s[62:63] offset:256
	s_add_u32 s62, s30, 0x18000
	s_addc_u32 s63, s31, 0
	v_lshlrev_b32_e32 v194, 16, v236
	v_lshlrev_b32_e32 v248, 16, v237
	v_and_b32_e32 v195, 0xffff0000, v236
	v_and_b32_e32 v249, 0xffff0000, v237
	v_pk_mul_f32 v[104:105], v[104:105], v[194:195]
	v_pk_mul_f32 v[106:107], v[106:107], v[248:249]
	v_lshlrev_b32_e32 v194, 16, v238
	v_lshlrev_b32_e32 v248, 16, v239
	v_and_b32_e32 v195, 0xffff0000, v238
	v_and_b32_e32 v249, 0xffff0000, v239
	v_pk_mul_f32 v[100:101], v[100:101], v[194:195]
	v_pk_mul_f32 v[102:103], v[102:103], v[248:249]
	v_cvt_pk_bf16_f32 v236, v104, v105
	v_cvt_pk_bf16_f32 v237, v106, v107
	v_cvt_pk_bf16_f32 v238, v100, v101
	v_cvt_pk_bf16_f32 v239, v102, v103
	global_store_dwordx4 v148, v[236:239], s[62:63]
	v_lshlrev_b32_e32 v194, 16, v240
	v_lshlrev_b32_e32 v248, 16, v241
	v_and_b32_e32 v195, 0xffff0000, v240
	v_and_b32_e32 v249, 0xffff0000, v241
	v_pk_mul_f32 v[72:73], v[72:73], v[194:195]
	v_pk_mul_f32 v[74:75], v[74:75], v[248:249]
	v_lshlrev_b32_e32 v194, 16, v242
	v_lshlrev_b32_e32 v248, 16, v243
	v_and_b32_e32 v195, 0xffff0000, v242
	v_and_b32_e32 v249, 0xffff0000, v243
	v_pk_mul_f32 v[68:69], v[68:69], v[194:195]
	v_pk_mul_f32 v[70:71], v[70:71], v[248:249]
	v_cvt_pk_bf16_f32 v240, v72, v73
	v_cvt_pk_bf16_f32 v241, v74, v75
	v_cvt_pk_bf16_f32 v242, v68, v69
	v_cvt_pk_bf16_f32 v243, v70, v71
	global_store_dwordx4 v148, v[240:243], s[62:63] offset:256
	s_add_u32 s62, s30, 0x40000
	s_addc_u32 s63, s31, 0
	v_lshlrev_b32_e32 v194, 16, v244
	v_lshlrev_b32_e32 v248, 16, v245
	v_and_b32_e32 v195, 0xffff0000, v244
	v_and_b32_e32 v249, 0xffff0000, v245
	v_pk_mul_f32 v[64:65], v[64:65], v[194:195]
	v_pk_mul_f32 v[66:67], v[66:67], v[248:249]
	v_lshlrev_b32_e32 v194, 16, v246
	v_lshlrev_b32_e32 v248, 16, v247
	v_and_b32_e32 v195, 0xffff0000, v246
	v_and_b32_e32 v249, 0xffff0000, v247
	v_pk_mul_f32 v[60:61], v[60:61], v[194:195]
	v_pk_mul_f32 v[62:63], v[62:63], v[248:249]
	v_cvt_pk_bf16_f32 v244, v64, v65
	v_cvt_pk_bf16_f32 v245, v66, v67
	v_cvt_pk_bf16_f32 v246, v60, v61
	v_cvt_pk_bf16_f32 v247, v62, v63
	global_store_dwordx4 v148, v[244:247], s[62:63]
	v_lshlrev_b32_e32 v194, 16, v178
	v_lshlrev_b32_e32 v248, 16, v179
	v_and_b32_e32 v195, 0xffff0000, v178
	v_and_b32_e32 v249, 0xffff0000, v179
	v_pk_mul_f32 v[32:33], v[32:33], v[194:195]
	v_pk_mul_f32 v[34:35], v[34:35], v[248:249]
	v_lshlrev_b32_e32 v194, 16, v180
	v_lshlrev_b32_e32 v248, 16, v181
	v_and_b32_e32 v195, 0xffff0000, v180
	v_and_b32_e32 v249, 0xffff0000, v181
	v_pk_mul_f32 v[28:29], v[28:29], v[194:195]
	v_pk_mul_f32 v[30:31], v[30:31], v[248:249]
	v_cvt_pk_bf16_f32 v178, v32, v33
	v_cvt_pk_bf16_f32 v179, v34, v35
	v_cvt_pk_bf16_f32 v180, v28, v29
	v_cvt_pk_bf16_f32 v181, v30, v31
	global_store_dwordx4 v148, v[178:181], s[62:63] offset:256
	s_add_u32 s62, s30, 0x48000
	s_addc_u32 s63, s31, 0
	v_lshlrev_b32_e32 v194, 16, v182
	v_lshlrev_b32_e32 v248, 16, v183
	v_and_b32_e32 v195, 0xffff0000, v182
	v_and_b32_e32 v249, 0xffff0000, v183
	v_pk_mul_f32 v[56:57], v[56:57], v[194:195]
	v_pk_mul_f32 v[58:59], v[58:59], v[248:249]
	v_lshlrev_b32_e32 v194, 16, v184
	v_lshlrev_b32_e32 v248, 16, v185
	v_and_b32_e32 v195, 0xffff0000, v184
	v_and_b32_e32 v249, 0xffff0000, v185
	v_pk_mul_f32 v[52:53], v[52:53], v[194:195]
	v_pk_mul_f32 v[54:55], v[54:55], v[248:249]
	v_cvt_pk_bf16_f32 v182, v56, v57
	v_cvt_pk_bf16_f32 v183, v58, v59
	v_cvt_pk_bf16_f32 v184, v52, v53
	v_cvt_pk_bf16_f32 v185, v54, v55
	global_store_dwordx4 v148, v[182:185], s[62:63]
	v_lshlrev_b32_e32 v194, 16, v186
	v_lshlrev_b32_e32 v248, 16, v187
	v_and_b32_e32 v195, 0xffff0000, v186
	v_and_b32_e32 v249, 0xffff0000, v187
	v_pk_mul_f32 v[24:25], v[24:25], v[194:195]
	v_pk_mul_f32 v[26:27], v[26:27], v[248:249]
	v_lshlrev_b32_e32 v194, 16, v188
	v_lshlrev_b32_e32 v248, 16, v189
	v_and_b32_e32 v195, 0xffff0000, v188
	v_and_b32_e32 v249, 0xffff0000, v189
	v_pk_mul_f32 v[20:21], v[20:21], v[194:195]
	v_pk_mul_f32 v[22:23], v[22:23], v[248:249]
	v_cvt_pk_bf16_f32 v186, v24, v25
	v_cvt_pk_bf16_f32 v187, v26, v27
	v_cvt_pk_bf16_f32 v188, v20, v21
	v_cvt_pk_bf16_f32 v189, v22, v23
	global_store_dwordx4 v148, v[186:189], s[62:63] offset:256
	s_add_u32 s62, s30, 0x50000
	s_addc_u32 s63, s31, 0
	v_lshlrev_b32_e32 v194, 16, v190
	v_lshlrev_b32_e32 v248, 16, v191
	v_and_b32_e32 v195, 0xffff0000, v190
	v_and_b32_e32 v249, 0xffff0000, v191
	v_pk_mul_f32 v[48:49], v[48:49], v[194:195]
	v_pk_mul_f32 v[50:51], v[50:51], v[248:249]
	v_lshlrev_b32_e32 v194, 16, v192
	v_lshlrev_b32_e32 v248, 16, v193
	v_and_b32_e32 v195, 0xffff0000, v192
	v_and_b32_e32 v249, 0xffff0000, v193
	v_pk_mul_f32 v[44:45], v[44:45], v[194:195]
	v_pk_mul_f32 v[46:47], v[46:47], v[248:249]
	v_cvt_pk_bf16_f32 v190, v48, v49
	v_cvt_pk_bf16_f32 v191, v50, v51
	v_cvt_pk_bf16_f32 v192, v44, v45
	v_cvt_pk_bf16_f32 v193, v46, v47
	global_store_dwordx4 v148, v[190:193], s[62:63]
	v_lshlrev_b32_e32 v194, 16, v162
	v_lshlrev_b32_e32 v248, 16, v163
	v_and_b32_e32 v195, 0xffff0000, v162
	v_and_b32_e32 v249, 0xffff0000, v163
	v_pk_mul_f32 v[16:17], v[16:17], v[194:195]
	v_pk_mul_f32 v[18:19], v[18:19], v[248:249]
	v_lshlrev_b32_e32 v194, 16, v164
	v_lshlrev_b32_e32 v248, 16, v165
	v_and_b32_e32 v195, 0xffff0000, v164
	v_and_b32_e32 v249, 0xffff0000, v165
	v_pk_mul_f32 v[12:13], v[12:13], v[194:195]
	v_pk_mul_f32 v[14:15], v[14:15], v[248:249]
	v_cvt_pk_bf16_f32 v162, v16, v17
	v_cvt_pk_bf16_f32 v163, v18, v19
	v_cvt_pk_bf16_f32 v164, v12, v13
	v_cvt_pk_bf16_f32 v165, v14, v15
	global_store_dwordx4 v148, v[162:165], s[62:63] offset:256
	s_add_u32 s62, s30, 0x58000
	s_addc_u32 s63, s31, 0
	v_lshlrev_b32_e32 v194, 16, v166
	v_lshlrev_b32_e32 v248, 16, v167
	v_and_b32_e32 v195, 0xffff0000, v166
	v_and_b32_e32 v249, 0xffff0000, v167
	v_pk_mul_f32 v[40:41], v[40:41], v[194:195]
	v_pk_mul_f32 v[42:43], v[42:43], v[248:249]
	v_lshlrev_b32_e32 v194, 16, v168
	v_lshlrev_b32_e32 v248, 16, v169
	v_and_b32_e32 v195, 0xffff0000, v168
	v_and_b32_e32 v249, 0xffff0000, v169
	v_pk_mul_f32 v[36:37], v[36:37], v[194:195]
	v_pk_mul_f32 v[38:39], v[38:39], v[248:249]
	v_cvt_pk_bf16_f32 v166, v40, v41
	v_cvt_pk_bf16_f32 v167, v42, v43
	v_cvt_pk_bf16_f32 v168, v36, v37
	v_cvt_pk_bf16_f32 v169, v38, v39
	global_store_dwordx4 v148, v[166:169], s[62:63]
	v_lshlrev_b32_e32 v194, 16, v170
	v_lshlrev_b32_e32 v248, 16, v171
	v_and_b32_e32 v195, 0xffff0000, v170
	v_and_b32_e32 v249, 0xffff0000, v171
	v_pk_mul_f32 v[8:9], v[8:9], v[194:195]
	v_pk_mul_f32 v[10:11], v[10:11], v[248:249]
	v_lshlrev_b32_e32 v194, 16, v172
	v_lshlrev_b32_e32 v248, 16, v173
	v_and_b32_e32 v195, 0xffff0000, v172
	v_and_b32_e32 v249, 0xffff0000, v173
	v_pk_mul_f32 v[4:5], v[4:5], v[194:195]
	v_pk_mul_f32 v[6:7], v[6:7], v[248:249]
	v_cvt_pk_bf16_f32 v170, v8, v9
	v_cvt_pk_bf16_f32 v171, v10, v11
	v_cvt_pk_bf16_f32 v172, v4, v5
	v_cvt_pk_bf16_f32 v173, v6, v7
	global_store_dwordx4 v148, v[170:173], s[62:63] offset:256

.LBB0_746:
	v_lshl_add_u32 v172, s84, 8, v180
	v_lshl_or_b32 v173, s83, 8, v182
	v_xor_b32_e32 v176, 16, v207
	v_xor_b32_e32 v177, 32, v207
	v_lshlrev_b32_e32 v175, 10, v172
	v_add_u32_e32 v175, v175, v173
	v_lshlrev_b32_e32 v174, 2, v175
	v_lshlrev_b32_e32 v175, 1, v175
	v_lshlrev_b32_e32 v173, 2, v173
	v_lshlrev_b32_e32 v172, 2, v172
	v_lshlrev_b32_e32 v176, 2, v176
	v_lshlrev_b32_e32 v177, 2, v177
	global_load_dwordx4 v[62:65], v173, s[4:5]
	global_load_dwordx4 v[58:61], v173, s[4:5] offset:16
	global_load_dwordx4 v[46:49], v173, s[4:5] offset:512
	global_load_dwordx4 v[34:37], v173, s[4:5] offset:528
	global_load_dwordx4 v[212:215], v174, s[2:3]
	global_load_dwordx4 v[216:219], v174, s[2:3] offset:16
	global_load_dwordx4 v[220:223], v174, s[2:3] offset:512
	global_load_dwordx4 v[224:227], v174, s[2:3] offset:528
	s_add_u32 s86, s2, 0x10000
	s_addc_u32 s87, s3, 0
	global_load_dwordx4 v[228:231], v174, s[86:87]
	global_load_dwordx4 v[232:235], v174, s[86:87] offset:16
	global_load_dwordx4 v[236:239], v174, s[86:87] offset:512
	global_load_dwordx4 v[240:243], v174, s[86:87] offset:528
	s_add_u32 s86, s2, 0x20000
	s_addc_u32 s87, s3, 0
	global_load_dwordx4 v[184:187], v174, s[86:87]
	global_load_dwordx4 v[188:191], v174, s[86:87] offset:16
	global_load_dwordx4 v[192:195], v174, s[86:87] offset:512
	global_load_dwordx4 v[244:247], v174, s[86:87] offset:528
	s_lshl_b32 s13, s83, 2
	s_or_b32 s50, s13, s78
	s_ashr_i32 s51, s50, 31
	s_lshl_b64 s[50:51], s[50:51], 17
	v_readlane_b32 s60, v251, 55
	v_readlane_b32 s61, v251, 56
	s_nop 3
	s_add_u32 s50, s60, s50
	s_addc_u32 s51, s61, s51
	s_waitcnt vmcnt(0)
	v_pk_add_f32 v[142:143], v[142:143], v[212:213]
	v_pk_add_f32 v[144:145], v[144:145], v[214:215]
	v_pk_add_f32 v[138:139], v[138:139], v[216:217]
	v_pk_add_f32 v[140:141], v[140:141], v[218:219]
	v_pk_add_f32 v[134:135], v[134:135], v[220:221]
	v_pk_add_f32 v[136:137], v[136:137], v[222:223]
	v_pk_add_f32 v[130:131], v[130:131], v[224:225]
	v_pk_add_f32 v[132:133], v[132:133], v[226:227]
	global_store_dwordx4 v174, v[142:145], s[16:17]
	global_store_dwordx4 v174, v[138:141], s[16:17] offset:16
	global_store_dwordx4 v174, v[134:137], s[16:17] offset:512
	global_store_dwordx4 v174, v[130:133], s[16:17] offset:528
	v_mul_f32_e32 v149, v145, v145
	v_mul_f32_e32 v148, v143, v143
	v_fmac_f32_e32 v148, v142, v142
	v_fmac_f32_e32 v149, v144, v144
	v_add_f32_e32 v148, v148, v149
	v_mul_f32_e32 v149, v139, v139
	v_fmac_f32_e32 v149, v138, v138
	v_add_f32_e32 v148, v148, v149
	v_mul_f32_e32 v149, v141, v141
	v_fmac_f32_e32 v149, v140, v140
	v_add_f32_e32 v178, v149, v148
	v_mul_f32_e32 v149, v137, v137
	v_mul_f32_e32 v148, v135, v135
	v_fmac_f32_e32 v148, v134, v134
	v_fmac_f32_e32 v149, v136, v136
	v_add_f32_e32 v148, v148, v149
	v_mul_f32_e32 v149, v131, v131
	v_fmac_f32_e32 v149, v130, v130
	v_add_f32_e32 v148, v148, v149
	v_mul_f32_e32 v149, v133, v133
	v_fmac_f32_e32 v149, v132, v132
	v_add_f32_e32 v148, v149, v148
	v_add_f32_e32 v178, v178, v148
	ds_bpermute_b32 v179, v176, v178
	v_pk_mul_f32 v[212:213], v[62:63], v[142:143]
	v_pk_mul_f32 v[214:215], v[64:65], v[144:145]
	v_pk_mul_f32 v[216:217], v[58:59], v[138:139]
	v_pk_mul_f32 v[218:219], v[60:61], v[140:141]
	v_pk_mul_f32 v[220:221], v[46:47], v[134:135]
	v_pk_mul_f32 v[222:223], v[48:49], v[136:137]
	v_pk_mul_f32 v[224:225], v[34:35], v[130:131]
	v_pk_mul_f32 v[226:227], v[36:37], v[132:133]
	s_waitcnt lgkmcnt(0)
	v_add_f32_e32 v178, v178, v179
	ds_bpermute_b32 v248, v177, v178
	v_cvt_pk_bf16_f32 v212, v212, v213
	v_cvt_pk_bf16_f32 v213, v214, v215
	v_cvt_pk_bf16_f32 v214, v216, v217
	v_cvt_pk_bf16_f32 v215, v218, v219
	v_cvt_pk_bf16_f32 v220, v220, v221
	v_cvt_pk_bf16_f32 v221, v222, v223
	v_cvt_pk_bf16_f32 v222, v224, v225
	v_cvt_pk_bf16_f32 v223, v226, v227
	global_store_dwordx4 v175, v[212:215], s[34:35]
	global_store_dwordx4 v175, v[220:223], s[34:35] offset:256
	s_waitcnt lgkmcnt(0)
	v_add_f32_e32 v178, v178, v248
	s_and_saveexec_b64 s[58:59], s[40:41]
	global_store_dword v172, v178, s[50:51]
	s_or_b64 exec, exec, s[58:59]
	v_pk_add_f32 v[126:127], v[126:127], v[228:229]
	v_pk_add_f32 v[128:129], v[128:129], v[230:231]
	v_pk_add_f32 v[122:123], v[122:123], v[232:233]
	v_pk_add_f32 v[124:125], v[124:125], v[234:235]
	v_pk_add_f32 v[118:119], v[118:119], v[236:237]
	v_pk_add_f32 v[120:121], v[120:121], v[238:239]
	v_pk_add_f32 v[114:115], v[114:115], v[240:241]
	v_pk_add_f32 v[116:117], v[116:117], v[242:243]
	s_add_u32 s88, s16, 0x10000
	s_addc_u32 s89, s17, 0
	s_add_u32 s90, s34, 0x8000
	s_addc_u32 s91, s35, 0
	global_store_dwordx4 v174, v[126:129], s[88:89]
	global_store_dwordx4 v174, v[122:125], s[88:89] offset:16
	global_store_dwordx4 v174, v[118:121], s[88:89] offset:512
	global_store_dwordx4 v174, v[114:117], s[88:89] offset:528
	v_mul_f32_e32 v149, v129, v129
	v_mul_f32_e32 v148, v127, v127
	v_fmac_f32_e32 v148, v126, v126
	v_fmac_f32_e32 v149, v128, v128
	v_add_f32_e32 v148, v148, v149
	v_mul_f32_e32 v149, v123, v123
	v_fmac_f32_e32 v149, v122, v122
	v_add_f32_e32 v148, v148, v149
	v_mul_f32_e32 v149, v125, v125
	v_fmac_f32_e32 v149, v124, v124
	v_add_f32_e32 v178, v149, v148
	v_mul_f32_e32 v149, v121, v121
	v_mul_f32_e32 v148, v119, v119
	v_fmac_f32_e32 v148, v118, v118
	v_fmac_f32_e32 v149, v120, v120
	v_add_f32_e32 v148, v148, v149
	v_mul_f32_e32 v149, v115, v115
	v_fmac_f32_e32 v149, v114, v114
	v_add_f32_e32 v148, v148, v149
	v_mul_f32_e32 v149, v117, v117
	v_fmac_f32_e32 v149, v116, v116
	v_add_f32_e32 v148, v149, v148
	v_add_f32_e32 v178, v178, v148
	ds_bpermute_b32 v179, v176, v178
	v_pk_mul_f32 v[228:229], v[62:63], v[126:127]
	v_pk_mul_f32 v[230:231], v[64:65], v[128:129]
	v_pk_mul_f32 v[232:233], v[58:59], v[122:123]
	v_pk_mul_f32 v[234:235], v[60:61], v[124:125]
	v_pk_mul_f32 v[236:237], v[46:47], v[118:119]
	v_pk_mul_f32 v[238:239], v[48:49], v[120:121]
	v_pk_mul_f32 v[240:241], v[34:35], v[114:115]
	v_pk_mul_f32 v[242:243], v[36:37], v[116:117]
	s_waitcnt lgkmcnt(0)
	v_add_f32_e32 v178, v178, v179
	ds_bpermute_b32 v248, v177, v178
	v_cvt_pk_bf16_f32 v228, v228, v229
	v_cvt_pk_bf16_f32 v229, v230, v231
	v_cvt_pk_bf16_f32 v230, v232, v233
	v_cvt_pk_bf16_f32 v231, v234, v235
	v_cvt_pk_bf16_f32 v236, v236, v237
	v_cvt_pk_bf16_f32 v237, v238, v239
	v_cvt_pk_bf16_f32 v238, v240, v241
	v_cvt_pk_bf16_f32 v239, v242, v243
	global_store_dwordx4 v175, v[228:231], s[90:91]
	global_store_dwordx4 v175, v[236:239], s[90:91] offset:256
	s_waitcnt lgkmcnt(0)
	v_add_f32_e32 v178, v178, v248
	s_and_saveexec_b64 s[58:59], s[40:41]
	global_store_dword v172, v178, s[50:51] offset:64
	s_or_b64 exec, exec, s[58:59]
	v_pk_add_f32 v[110:111], v[110:111], v[184:185]
	v_pk_add_f32 v[112:113], v[112:113], v[186:187]
	v_pk_add_f32 v[106:107], v[106:107], v[188:189]
	v_pk_add_f32 v[108:109], v[108:109], v[190:191]
	v_pk_add_f32 v[102:103], v[102:103], v[192:193]
	v_pk_add_f32 v[104:105], v[104:105], v[194:195]
	v_pk_add_f32 v[98:99], v[98:99], v[244:245]
	v_pk_add_f32 v[100:101], v[100:101], v[246:247]
	s_add_u32 s88, s16, 0x20000
	s_addc_u32 s89, s17, 0
	s_add_u32 s90, s34, 0x10000
	s_addc_u32 s91, s35, 0
	global_store_dwordx4 v174, v[110:113], s[88:89]
	global_store_dwordx4 v174, v[106:109], s[88:89] offset:16
	global_store_dwordx4 v174, v[102:105], s[88:89] offset:512
	global_store_dwordx4 v174, v[98:101], s[88:89] offset:528
	v_mul_f32_e32 v149, v113, v113
	v_mul_f32_e32 v148, v111, v111
	v_fmac_f32_e32 v148, v110, v110
	v_fmac_f32_e32 v149, v112, v112
	v_add_f32_e32 v148, v148, v149
	v_mul_f32_e32 v149, v107, v107
	v_fmac_f32_e32 v149, v106, v106
	v_add_f32_e32 v148, v148, v149
	v_mul_f32_e32 v149, v109, v109
	v_fmac_f32_e32 v149, v108, v108
	v_add_f32_e32 v178, v149, v148
	v_mul_f32_e32 v149, v105, v105
	v_mul_f32_e32 v148, v103, v103
	v_fmac_f32_e32 v148, v102, v102
	v_fmac_f32_e32 v149, v104, v104
	v_add_f32_e32 v148, v148, v149
	v_mul_f32_e32 v149, v99, v99
	v_fmac_f32_e32 v149, v98, v98
	v_add_f32_e32 v148, v148, v149
	v_mul_f32_e32 v149, v101, v101
	v_fmac_f32_e32 v149, v100, v100
	v_add_f32_e32 v148, v149, v148
	v_add_f32_e32 v178, v178, v148
	ds_bpermute_b32 v179, v176, v178
	v_pk_mul_f32 v[184:185], v[62:63], v[110:111]
	v_pk_mul_f32 v[186:187], v[64:65], v[112:113]
	v_pk_mul_f32 v[188:189], v[58:59], v[106:107]
	v_pk_mul_f32 v[190:191], v[60:61], v[108:109]
	v_pk_mul_f32 v[192:193], v[46:47], v[102:103]
	v_pk_mul_f32 v[194:195], v[48:49], v[104:105]
	v_pk_mul_f32 v[244:245], v[34:35], v[98:99]
	v_pk_mul_f32 v[246:247], v[36:37], v[100:101]
	s_waitcnt lgkmcnt(0)
	v_add_f32_e32 v178, v178, v179
	ds_bpermute_b32 v248, v177, v178
	v_cvt_pk_bf16_f32 v184, v184, v185
	v_cvt_pk_bf16_f32 v185, v186, v187
	v_cvt_pk_bf16_f32 v186, v188, v189
	v_cvt_pk_bf16_f32 v187, v190, v191
	v_cvt_pk_bf16_f32 v192, v192, v193
	v_cvt_pk_bf16_f32 v193, v194, v195
	v_cvt_pk_bf16_f32 v194, v244, v245
	v_cvt_pk_bf16_f32 v195, v246, v247
	global_store_dwordx4 v175, v[184:187], s[90:91]
	global_store_dwordx4 v175, v[192:195], s[90:91] offset:256
	s_waitcnt lgkmcnt(0)
	v_add_f32_e32 v178, v178, v248
	s_and_saveexec_b64 s[58:59], s[40:41]
	global_store_dword v172, v178, s[50:51] offset:128
	s_or_b64 exec, exec, s[58:59]
	s_add_u32 s86, s2, 0x30000
	s_addc_u32 s87, s3, 0
	global_load_dwordx4 v[212:215], v174, s[86:87]
	global_load_dwordx4 v[216:219], v174, s[86:87] offset:16
	global_load_dwordx4 v[220:223], v174, s[86:87] offset:512
	global_load_dwordx4 v[224:227], v174, s[86:87] offset:528
	s_add_u32 s86, s2, 0x80000
	s_addc_u32 s87, s3, 0
	global_load_dwordx4 v[228:231], v174, s[86:87]
	global_load_dwordx4 v[232:235], v174, s[86:87] offset:16
	global_load_dwordx4 v[236:239], v174, s[86:87] offset:512
	global_load_dwordx4 v[240:243], v174, s[86:87] offset:528
	s_add_u32 s86, s2, 0x90000
	s_addc_u32 s87, s3, 0
	global_load_dwordx4 v[184:187], v174, s[86:87]
	global_load_dwordx4 v[188:191], v174, s[86:87] offset:16
	global_load_dwordx4 v[192:195], v174, s[86:87] offset:512
	global_load_dwordx4 v[244:247], v174, s[86:87] offset:528
	s_waitcnt vmcnt(0)
	v_pk_add_f32 v[94:95], v[94:95], v[212:213]
	v_pk_add_f32 v[96:97], v[96:97], v[214:215]
	v_pk_add_f32 v[90:91], v[90:91], v[216:217]
	v_pk_add_f32 v[92:93], v[92:93], v[218:219]
	v_pk_add_f32 v[86:87], v[86:87], v[220:221]
	v_pk_add_f32 v[88:89], v[88:89], v[222:223]
	v_pk_add_f32 v[82:83], v[82:83], v[224:225]
	v_pk_add_f32 v[84:85], v[84:85], v[226:227]
	s_add_u32 s88, s16, 0x30000
	s_addc_u32 s89, s17, 0
	s_add_u32 s90, s34, 0x18000
	s_addc_u32 s91, s35, 0
	global_store_dwordx4 v174, v[94:97], s[88:89]
	global_store_dwordx4 v174, v[90:93], s[88:89] offset:16
	global_store_dwordx4 v174, v[86:89], s[88:89] offset:512
	global_store_dwordx4 v174, v[82:85], s[88:89] offset:528
	v_mul_f32_e32 v149, v97, v97
	v_mul_f32_e32 v148, v95, v95
	v_fmac_f32_e32 v148, v94, v94
	v_fmac_f32_e32 v149, v96, v96
	v_add_f32_e32 v148, v148, v149
	v_mul_f32_e32 v149, v91, v91
	v_fmac_f32_e32 v149, v90, v90
	v_add_f32_e32 v148, v148, v149
	v_mul_f32_e32 v149, v93, v93
	v_fmac_f32_e32 v149, v92, v92
	v_add_f32_e32 v178, v149, v148
	v_mul_f32_e32 v149, v89, v89
	v_mul_f32_e32 v148, v87, v87
	v_fmac_f32_e32 v148, v86, v86
	v_fmac_f32_e32 v149, v88, v88
	v_add_f32_e32 v148, v148, v149
	v_mul_f32_e32 v149, v83, v83
	v_fmac_f32_e32 v149, v82, v82
	v_add_f32_e32 v148, v148, v149
	v_mul_f32_e32 v149, v85, v85
	v_fmac_f32_e32 v149, v84, v84
	v_add_f32_e32 v148, v149, v148
	v_add_f32_e32 v178, v178, v148
	ds_bpermute_b32 v179, v176, v178
	v_pk_mul_f32 v[212:213], v[62:63], v[94:95]
	v_pk_mul_f32 v[214:215], v[64:65], v[96:97]
	v_pk_mul_f32 v[216:217], v[58:59], v[90:91]
	v_pk_mul_f32 v[218:219], v[60:61], v[92:93]
	v_pk_mul_f32 v[220:221], v[46:47], v[86:87]
	v_pk_mul_f32 v[222:223], v[48:49], v[88:89]
	v_pk_mul_f32 v[224:225], v[34:35], v[82:83]
	v_pk_mul_f32 v[226:227], v[36:37], v[84:85]
	s_waitcnt lgkmcnt(0)
	v_add_f32_e32 v178, v178, v179
	ds_bpermute_b32 v248, v177, v178
	v_cvt_pk_bf16_f32 v212, v212, v213
	v_cvt_pk_bf16_f32 v213, v214, v215
	v_cvt_pk_bf16_f32 v214, v216, v217
	v_cvt_pk_bf16_f32 v215, v218, v219
	v_cvt_pk_bf16_f32 v220, v220, v221
	v_cvt_pk_bf16_f32 v221, v222, v223
	v_cvt_pk_bf16_f32 v222, v224, v225
	v_cvt_pk_bf16_f32 v223, v226, v227
	global_store_dwordx4 v175, v[212:215], s[90:91]
	global_store_dwordx4 v175, v[220:223], s[90:91] offset:256
	s_waitcnt lgkmcnt(0)
	v_add_f32_e32 v178, v178, v248
	s_and_saveexec_b64 s[58:59], s[40:41]
	global_store_dword v172, v178, s[50:51] offset:192
	s_or_b64 exec, exec, s[58:59]
	v_pk_add_f32 v[78:79], v[78:79], v[228:229]
	v_pk_add_f32 v[80:81], v[80:81], v[230:231]
	v_pk_add_f32 v[74:75], v[74:75], v[232:233]
	v_pk_add_f32 v[76:77], v[76:77], v[234:235]
	v_pk_add_f32 v[70:71], v[70:71], v[236:237]
	v_pk_add_f32 v[72:73], v[72:73], v[238:239]
	v_pk_add_f32 v[66:67], v[66:67], v[240:241]
	v_pk_add_f32 v[68:69], v[68:69], v[242:243]
	s_add_u32 s88, s16, 0x80000
	s_addc_u32 s89, s17, 0
	s_add_u32 s90, s34, 0x40000
	s_addc_u32 s91, s35, 0
	global_store_dwordx4 v174, v[78:81], s[88:89]
	global_store_dwordx4 v174, v[74:77], s[88:89] offset:16
	global_store_dwordx4 v174, v[70:73], s[88:89] offset:512
	global_store_dwordx4 v174, v[66:69], s[88:89] offset:528
	v_mul_f32_e32 v149, v81, v81
	v_mul_f32_e32 v148, v79, v79
	v_fmac_f32_e32 v148, v78, v78
	v_fmac_f32_e32 v149, v80, v80
	v_add_f32_e32 v148, v148, v149
	v_mul_f32_e32 v149, v75, v75
	v_fmac_f32_e32 v149, v74, v74
	v_add_f32_e32 v148, v148, v149
	v_mul_f32_e32 v149, v77, v77
	v_fmac_f32_e32 v149, v76, v76
	v_add_f32_e32 v178, v149, v148
	v_mul_f32_e32 v149, v73, v73
	v_mul_f32_e32 v148, v71, v71
	v_fmac_f32_e32 v148, v70, v70
	v_fmac_f32_e32 v149, v72, v72
	v_add_f32_e32 v148, v148, v149
	v_mul_f32_e32 v149, v67, v67
	v_fmac_f32_e32 v149, v66, v66
	v_add_f32_e32 v148, v148, v149
	v_mul_f32_e32 v149, v69, v69
	v_fmac_f32_e32 v149, v68, v68
	v_add_f32_e32 v148, v149, v148
	v_add_f32_e32 v178, v178, v148
	ds_bpermute_b32 v179, v176, v178
	v_pk_mul_f32 v[228:229], v[62:63], v[78:79]
	v_pk_mul_f32 v[230:231], v[64:65], v[80:81]
	v_pk_mul_f32 v[232:233], v[58:59], v[74:75]
	v_pk_mul_f32 v[234:235], v[60:61], v[76:77]
	v_pk_mul_f32 v[236:237], v[46:47], v[70:71]
	v_pk_mul_f32 v[238:239], v[48:49], v[72:73]
	v_pk_mul_f32 v[240:241], v[34:35], v[66:67]
	v_pk_mul_f32 v[242:243], v[36:37], v[68:69]
	s_waitcnt lgkmcnt(0)
	v_add_f32_e32 v178, v178, v179
	ds_bpermute_b32 v248, v177, v178
	v_cvt_pk_bf16_f32 v228, v228, v229
	v_cvt_pk_bf16_f32 v229, v230, v231
	v_cvt_pk_bf16_f32 v230, v232, v233
	v_cvt_pk_bf16_f32 v231, v234, v235
	v_cvt_pk_bf16_f32 v236, v236, v237
	v_cvt_pk_bf16_f32 v237, v238, v239
	v_cvt_pk_bf16_f32 v238, v240, v241
	v_cvt_pk_bf16_f32 v239, v242, v243
	global_store_dwordx4 v175, v[228:231], s[90:91]
	global_store_dwordx4 v175, v[236:239], s[90:91] offset:256
	s_waitcnt lgkmcnt(0)
	v_add_f32_e32 v178, v178, v248
	s_and_saveexec_b64 s[58:59], s[40:41]
	global_store_dword v172, v178, s[50:51] offset:512
	s_or_b64 exec, exec, s[58:59]
	v_pk_add_f32 v[54:55], v[54:55], v[184:185]
	v_pk_add_f32 v[56:57], v[56:57], v[186:187]
	v_pk_add_f32 v[50:51], v[50:51], v[188:189]
	v_pk_add_f32 v[52:53], v[52:53], v[190:191]
	v_pk_add_f32 v[42:43], v[42:43], v[192:193]
	v_pk_add_f32 v[44:45], v[44:45], v[194:195]
	v_pk_add_f32 v[38:39], v[38:39], v[244:245]
	v_pk_add_f32 v[40:41], v[40:41], v[246:247]
	s_add_u32 s88, s16, 0x90000
	s_addc_u32 s89, s17, 0
	s_add_u32 s90, s34, 0x48000
	s_addc_u32 s91, s35, 0
	global_store_dwordx4 v174, v[54:57], s[88:89]
	global_store_dwordx4 v174, v[50:53], s[88:89] offset:16
	global_store_dwordx4 v174, v[42:45], s[88:89] offset:512
	global_store_dwordx4 v174, v[38:41], s[88:89] offset:528
	v_mul_f32_e32 v149, v57, v57
	v_mul_f32_e32 v148, v55, v55
	v_fmac_f32_e32 v148, v54, v54
	v_fmac_f32_e32 v149, v56, v56
	v_add_f32_e32 v148, v148, v149
	v_mul_f32_e32 v149, v51, v51
	v_fmac_f32_e32 v149, v50, v50
	v_add_f32_e32 v148, v148, v149
	v_mul_f32_e32 v149, v53, v53
	v_fmac_f32_e32 v149, v52, v52
	v_add_f32_e32 v178, v149, v148
	v_mul_f32_e32 v149, v45, v45
	v_mul_f32_e32 v148, v43, v43
	v_fmac_f32_e32 v148, v42, v42
	v_fmac_f32_e32 v149, v44, v44
	v_add_f32_e32 v148, v148, v149
	v_mul_f32_e32 v149, v39, v39
	v_fmac_f32_e32 v149, v38, v38
	v_add_f32_e32 v148, v148, v149
	v_mul_f32_e32 v149, v41, v41
	v_fmac_f32_e32 v149, v40, v40
	v_add_f32_e32 v148, v149, v148
	v_add_f32_e32 v178, v178, v148
	ds_bpermute_b32 v179, v176, v178
	v_pk_mul_f32 v[184:185], v[62:63], v[54:55]
	v_pk_mul_f32 v[186:187], v[64:65], v[56:57]
	v_pk_mul_f32 v[188:189], v[58:59], v[50:51]
	v_pk_mul_f32 v[190:191], v[60:61], v[52:53]
	v_pk_mul_f32 v[192:193], v[46:47], v[42:43]
	v_pk_mul_f32 v[194:195], v[48:49], v[44:45]
	v_pk_mul_f32 v[244:245], v[34:35], v[38:39]
	v_pk_mul_f32 v[246:247], v[36:37], v[40:41]
	s_waitcnt lgkmcnt(0)
	v_add_f32_e32 v178, v178, v179
	ds_bpermute_b32 v248, v177, v178
	v_cvt_pk_bf16_f32 v184, v184, v185
	v_cvt_pk_bf16_f32 v185, v186, v187
	v_cvt_pk_bf16_f32 v186, v188, v189
	v_cvt_pk_bf16_f32 v187, v190, v191
	v_cvt_pk_bf16_f32 v192, v192, v193
	v_cvt_pk_bf16_f32 v193, v194, v195
	v_cvt_pk_bf16_f32 v194, v244, v245
	v_cvt_pk_bf16_f32 v195, v246, v247
	global_store_dwordx4 v175, v[184:187], s[90:91]
	global_store_dwordx4 v175, v[192:195], s[90:91] offset:256
	s_waitcnt lgkmcnt(0)
	v_add_f32_e32 v178, v178, v248
	s_and_saveexec_b64 s[58:59], s[40:41]
	global_store_dword v172, v178, s[50:51] offset:576
	s_or_b64 exec, exec, s[58:59]
	s_add_u32 s86, s2, 0xa0000
	s_addc_u32 s87, s3, 0
	global_load_dwordx4 v[212:215], v174, s[86:87]
	global_load_dwordx4 v[216:219], v174, s[86:87] offset:16
	global_load_dwordx4 v[220:223], v174, s[86:87] offset:512
	global_load_dwordx4 v[224:227], v174, s[86:87] offset:528
	s_add_u32 s86, s2, 0xb0000
	s_addc_u32 s87, s3, 0
	global_load_dwordx4 v[228:231], v174, s[86:87]
	global_load_dwordx4 v[232:235], v174, s[86:87] offset:16
	global_load_dwordx4 v[236:239], v174, s[86:87] offset:512
	global_load_dwordx4 v[240:243], v174, s[86:87] offset:528
	s_waitcnt vmcnt(0)
	v_pk_add_f32 v[30:31], v[30:31], v[212:213]
	v_pk_add_f32 v[32:33], v[32:33], v[214:215]
	v_pk_add_f32 v[26:27], v[26:27], v[216:217]
	v_pk_add_f32 v[28:29], v[28:29], v[218:219]
	v_pk_add_f32 v[22:23], v[22:23], v[220:221]
	v_pk_add_f32 v[24:25], v[24:25], v[222:223]
	v_pk_add_f32 v[18:19], v[18:19], v[224:225]
	v_pk_add_f32 v[20:21], v[20:21], v[226:227]
	s_add_u32 s88, s16, 0xa0000
	s_addc_u32 s89, s17, 0
	s_add_u32 s90, s34, 0x50000
	s_addc_u32 s91, s35, 0
	global_store_dwordx4 v174, v[30:33], s[88:89]
	global_store_dwordx4 v174, v[26:29], s[88:89] offset:16
	global_store_dwordx4 v174, v[22:25], s[88:89] offset:512
	global_store_dwordx4 v174, v[18:21], s[88:89] offset:528
	v_mul_f32_e32 v149, v33, v33
	v_mul_f32_e32 v148, v31, v31
	v_fmac_f32_e32 v148, v30, v30
	v_fmac_f32_e32 v149, v32, v32
	v_add_f32_e32 v148, v148, v149
	v_mul_f32_e32 v149, v27, v27
	v_fmac_f32_e32 v149, v26, v26
	v_add_f32_e32 v148, v148, v149
	v_mul_f32_e32 v149, v29, v29
	v_fmac_f32_e32 v149, v28, v28
	v_add_f32_e32 v178, v149, v148
	v_mul_f32_e32 v149, v25, v25
	v_mul_f32_e32 v148, v23, v23
	v_fmac_f32_e32 v148, v22, v22
	v_fmac_f32_e32 v149, v24, v24
	v_add_f32_e32 v148, v148, v149
	v_mul_f32_e32 v149, v19, v19
	v_fmac_f32_e32 v149, v18, v18
	v_add_f32_e32 v148, v148, v149
	v_mul_f32_e32 v149, v21, v21
	v_fmac_f32_e32 v149, v20, v20
	v_add_f32_e32 v148, v149, v148
	v_add_f32_e32 v178, v178, v148
	ds_bpermute_b32 v179, v176, v178
	v_pk_mul_f32 v[212:213], v[62:63], v[30:31]
	v_pk_mul_f32 v[214:215], v[64:65], v[32:33]
	v_pk_mul_f32 v[216:217], v[58:59], v[26:27]
	v_pk_mul_f32 v[218:219], v[60:61], v[28:29]
	v_pk_mul_f32 v[220:221], v[46:47], v[22:23]
	v_pk_mul_f32 v[222:223], v[48:49], v[24:25]
	v_pk_mul_f32 v[224:225], v[34:35], v[18:19]
	v_pk_mul_f32 v[226:227], v[36:37], v[20:21]
	s_waitcnt lgkmcnt(0)
	v_add_f32_e32 v178, v178, v179
	ds_bpermute_b32 v248, v177, v178
	v_cvt_pk_bf16_f32 v212, v212, v213
	v_cvt_pk_bf16_f32 v213, v214, v215
	v_cvt_pk_bf16_f32 v214, v216, v217
	v_cvt_pk_bf16_f32 v215, v218, v219
	v_cvt_pk_bf16_f32 v220, v220, v221
	v_cvt_pk_bf16_f32 v221, v222, v223
	v_cvt_pk_bf16_f32 v222, v224, v225
	v_cvt_pk_bf16_f32 v223, v226, v227
	global_store_dwordx4 v175, v[212:215], s[90:91]
	global_store_dwordx4 v175, v[220:223], s[90:91] offset:256
	s_waitcnt lgkmcnt(0)
	v_add_f32_e32 v178, v178, v248
	s_and_saveexec_b64 s[58:59], s[40:41]
	global_store_dword v172, v178, s[50:51] offset:640
	s_or_b64 exec, exec, s[58:59]
	v_pk_add_f32 v[14:15], v[14:15], v[228:229]
	v_pk_add_f32 v[16:17], v[16:17], v[230:231]
	v_pk_add_f32 v[10:11], v[10:11], v[232:233]
	v_pk_add_f32 v[12:13], v[12:13], v[234:235]
	v_pk_add_f32 v[6:7], v[6:7], v[236:237]
	v_pk_add_f32 v[8:9], v[8:9], v[238:239]
	v_pk_add_f32 v[2:3], v[2:3], v[240:241]
	v_pk_add_f32 v[4:5], v[4:5], v[242:243]
	s_add_u32 s88, s16, 0xb0000
	s_addc_u32 s89, s17, 0
	s_add_u32 s90, s34, 0x58000
	s_addc_u32 s91, s35, 0
	global_store_dwordx4 v174, v[14:17], s[88:89]
	global_store_dwordx4 v174, v[10:13], s[88:89] offset:16
	global_store_dwordx4 v174, v[6:9], s[88:89] offset:512
	global_store_dwordx4 v174, v[2:5], s[88:89] offset:528
	v_mul_f32_e32 v149, v17, v17
	v_mul_f32_e32 v148, v15, v15
	v_fmac_f32_e32 v148, v14, v14
	v_fmac_f32_e32 v149, v16, v16
	v_add_f32_e32 v148, v148, v149
	v_mul_f32_e32 v149, v11, v11
	v_fmac_f32_e32 v149, v10, v10
	v_add_f32_e32 v148, v148, v149
	v_mul_f32_e32 v149, v13, v13
	v_fmac_f32_e32 v149, v12, v12
	v_add_f32_e32 v178, v149, v148
	v_mul_f32_e32 v149, v9, v9
	v_mul_f32_e32 v148, v7, v7
	v_fmac_f32_e32 v148, v6, v6
	v_fmac_f32_e32 v149, v8, v8
	v_add_f32_e32 v148, v148, v149
	v_mul_f32_e32 v149, v3, v3
	v_fmac_f32_e32 v149, v2, v2
	v_add_f32_e32 v148, v148, v149
	v_mul_f32_e32 v149, v5, v5
	v_fmac_f32_e32 v149, v4, v4
	v_add_f32_e32 v148, v149, v148
	v_add_f32_e32 v178, v178, v148
	ds_bpermute_b32 v179, v176, v178
	v_pk_mul_f32 v[228:229], v[62:63], v[14:15]
	v_pk_mul_f32 v[230:231], v[64:65], v[16:17]
	v_pk_mul_f32 v[232:233], v[58:59], v[10:11]
	v_pk_mul_f32 v[234:235], v[60:61], v[12:13]
	v_pk_mul_f32 v[236:237], v[46:47], v[6:7]
	v_pk_mul_f32 v[238:239], v[48:49], v[8:9]
	v_pk_mul_f32 v[240:241], v[34:35], v[2:3]
	v_pk_mul_f32 v[242:243], v[36:37], v[4:5]
	s_waitcnt lgkmcnt(0)
	v_add_f32_e32 v178, v178, v179
	ds_bpermute_b32 v248, v177, v178
	v_cvt_pk_bf16_f32 v228, v228, v229
	v_cvt_pk_bf16_f32 v229, v230, v231
	v_cvt_pk_bf16_f32 v230, v232, v233
	v_cvt_pk_bf16_f32 v231, v234, v235
	v_cvt_pk_bf16_f32 v236, v236, v237
	v_cvt_pk_bf16_f32 v237, v238, v239
	v_cvt_pk_bf16_f32 v238, v240, v241
	v_cvt_pk_bf16_f32 v239, v242, v243
	global_store_dwordx4 v175, v[228:231], s[90:91]
	global_store_dwordx4 v175, v[236:239], s[90:91] offset:256
	s_waitcnt lgkmcnt(0)
	v_add_f32_e32 v178, v178, v248
	s_and_saveexec_b64 s[58:59], s[40:41]
	global_store_dword v172, v178, s[50:51] offset:704
	s_or_b64 exec, exec, s[58:59]
	s_andn2_b64 vcc, exec, s[42:43]
	s_mov_b64 s[42:43], -1
	s_cbranch_vccnz .LBB0_734
	s_andn2_b64 vcc, exec, s[0:1]
	s_cbranch_vccnz .LBB0_733
	s_barrier
	s_branch .LBB0_733
